# GQA loop: softmax exps re-spread to about 4 per PV MFMA gap (order kept, only moved later)
# speedup vs baseline: 1.0049x; 1.0026x over previous
; template <int DK, int PAR, bool HASNEXT, bool LDK, bool LDV, bool STK> ...
;     ...
;     if (LDK) { ldk0 = *(const u32x4*)(kg0 + (size_t)(t + 3) * kstep); if (has1) ldk1 = *(const u32x4*)(kg1 + (size_t)(t + 3) * kstep); }
;     if (LDV) ldv = *(const u32x4*)(vg + (size_t)(t + 2) * vstep);
;     bf16x8 kf[A::NDS][2];
;     if (HASNEXT) {
; #pragma unroll
;         for (int ds = 0; ds < A::NDS; ++ds) {
;             kf[ds][0] = *(const LAS bf16x8*)(Kb + aoffk + ds * 32);
;             kf[ds][1] = *(const LAS bf16x8*)(Kb + aoffk + 32 * A::KSTR + ds * 32);
;         }
;     }
;     s16x4 vlo[4][2], vhi[4][2];
; #pragma unroll
;     for (int j = 0; j < 2; ++j) {
;         vlo[j][0] = vtr(Vb + aoffv + j * 16 * A::VSTR); vhi[j][0] = vtr(Vb + aoffv + (j * 16 + 8) * A::VSTR);
;         vlo[j][1] = vtr(Vb + aoffv + j * 16 * A::VSTR + 64); vhi[j][1] = vtr(Vb + aoffv + (j * 16 + 8) * A::VSTR + 64);
;     }
;     if (HASNEXT) {
;         f32x16 z;
; #pragma unroll
;         for (int i = 0; i < 16; ++i) z[i] = 0.f;
; #pragma unroll
;         for (int ds = 0; ds < A::NDS; ++ds) {
;             N0 = __builtin_amdgcn_mfma_f32_32x32x16_bf16(kf[ds][0], qf[ds], ds == 0 ? z : N0, 0, 0, 0);
;             N1 = __builtin_amdgcn_mfma_f32_32x32x16_bf16(kf[ds][1], qf[ds], ds == 0 ? z : N1, 0, 0, 0);
;         }
;     }
; #pragma unroll
;     for (int i = 0; i < 16; ++i) { l += C0[i]; l += C1[i]; }
;     bf16x8 pb[4];
;     { u32x4 w;
;       w.x = pk2(C0[0], C0[1]); w.y = pk2(C0[2], C0[3]); w.z = pk2(C0[4], C0[5]); w.w = pk2(C0[6], C0[7]); pb[0] = __builtin_bit_cast(bf16x8, w);
;       w.x = pk2(C0[8], C0[9]); w.y = pk2(C0[10], C0[11]); w.z = pk2(C0[12], C0[13]); w.w = pk2(C0[14], C0[15]); pb[1] = __builtin_bit_cast(bf16x8, w);
;       w.x = pk2(C1[0], C1[1]); w.y = pk2(C1[2], C1[3]); w.z = pk2(C1[4], C1[5]); w.w = pk2(C1[6], C1[7]); pb[2] = __builtin_bit_cast(bf16x8, w);
;       w.x = pk2(C1[8], C1[9]); w.y = pk2(C1[10], C1[11]); w.z = pk2(C1[12], C1[13]); w.w = pk2(C1[14], C1[15]); pb[3] = __builtin_bit_cast(bf16x8, w); }
;     if (HASNEXT) {
;         constexpr int VPER = (DK == 64) ? 6 : 4;
; #pragma unroll
;         for (int g = 0; g < 2 * A::NDS; ++g) { __builtin_amdgcn_sched_group_barrier(0x008, 1, 0); __builtin_amdgcn_sched_group_barrier(0x002, VPER, 0); }
;     }
;     asm volatile("" : "+v"(l));
;     __builtin_amdgcn_sched_barrier(0);
; #pragma unroll
.LBB0_779:
	s_setprio 1
	s_mov_b32 s11, 0x23a30000
	ds_read_b64_tr_b16 v[110:111], v96 offset:26624
	v_mfma_f32_32x32x16_bf16 v[48:63], v[216:219], v[76:79], 0
	v_lshl_add_u64 v[126:127], v[122:123], 0, s[8:9]
	v_add_co_u32_e32 v32, vcc, s11, v126
	v_lshl_add_u64 v[128:129], v[124:125], 0, s[8:9]
	s_nop 0
	v_addc_co_u32_e32 v33, vcc, 0, v127, vcc
	s_mov_b32 s11, 0x24aa8000
	global_load_dwordx4 v[88:91], v[32:33], off
	v_add_co_u32_e32 v32, vcc, s11, v128
	ds_read_b64_tr_b16 v[112:113], v96 offset:28160
	s_nop 0
	v_addc_co_u32_e32 v33, vcc, 0, v129, vcc
	global_load_dwordx4 v[92:95], v[32:33], off
	v_mfma_f32_32x32x16_bf16 v[32:47], v[220:223], v[76:79], 0
	v_add_f32_e32 v150, v146, v172
	v_add_f32_e32 v150, v132, v150
	v_add_f32_e32 v150, v148, v150
	v_add_f32_e32 v150, v133, v150
	v_add_f32_e32 v150, v158, v150
	v_add_f32_e32 v150, v134, v150
	ds_read_b64_tr_b16 v[106:107], v96 offset:26688
	v_mfma_f32_32x32x16_bf16 v[32:47], v[224:227], v[72:75], v[32:47]
	v_add_f32_e32 v150, v159, v150
	v_add_f32_e32 v150, v135, v150
	v_add_f32_e32 v150, v160, v150
	v_add_f32_e32 v150, v136, v150
	v_add_f32_e32 v150, v162, v150
	v_add_f32_e32 v150, v137, v150
	ds_read_b64_tr_b16 v[108:109], v96 offset:28224
	v_mfma_f32_32x32x16_bf16 v[48:63], v[228:231], v[72:75], v[48:63]
	s_waitcnt vmcnt(3)
	ds_write_b128 v130, v[80:83] offset:13312
	s_waitcnt vmcnt(2)
	ds_write_b128 v117, v[84:87] offset:38912
	v_add_f32_e32 v150, v164, v150
	v_add_f32_e32 v150, v139, v150
	v_add_f32_e32 v150, v166, v150
	v_add_f32_e32 v150, v141, v150
	v_add_f32_e32 v150, v161, v150
	v_add_f32_e32 v150, v138, v150
	ds_read_b64_tr_b16 v[102:103], v96 offset:29696
	v_mfma_f32_32x32x16_bf16 v[32:47], v[236:239], v[68:71], v[32:47]
	v_add_f32_e32 v150, v163, v150
	v_add_f32_e32 v150, v140, v150
	v_add_f32_e32 v150, v165, v150
	v_add_f32_e32 v150, v142, v150
	v_add_f32_e32 v150, v168, v150
	v_add_f32_e32 v150, v143, v150
	ds_read_b64_tr_b16 v[104:105], v96 offset:31232
	v_mfma_f32_32x32x16_bf16 v[48:63], v[240:243], v[68:71], v[48:63]
	v_add_f32_e32 v150, v167, v150
	v_add_f32_e32 v150, v144, v150
	v_add_f32_e32 v150, v169, v150
	v_add_f32_e32 v150, v145, v150
	ds_read_b64_tr_b16 v[98:99], v96 offset:29760
	ds_read_b64_tr_b16 v[100:101], v96 offset:31296
	v_add_f32_e32 v150, v170, v150
	v_add_f32_e32 v150, v147, v150
	v_mfma_f32_32x32x16_bf16 v[32:47], v[244:247], v[64:67], v[32:47]
	v_add_f32_e32 v150, v171, v150
	v_add_f32_e32 v152, v149, v150
	v_cvt_pk_bf16_f32 v182, v146, v148
	v_cvt_pk_bf16_f32 v183, v158, v159
	v_cvt_pk_bf16_f32 v184, v160, v162
	v_cvt_pk_bf16_f32 v185, v164, v166
	v_mfma_f32_32x32x16_bf16 v[48:63], v[248:251], v[64:67], v[48:63]
	v_cvt_pk_bf16_f32 v158, v161, v163
	v_cvt_pk_bf16_f32 v159, v165, v168
	v_cvt_pk_bf16_f32 v160, v167, v169
	v_cvt_pk_bf16_f32 v161, v170, v171
	v_cvt_pk_bf16_f32 v132, v132, v133
	v_cvt_pk_bf16_f32 v133, v134, v135
	v_cvt_pk_bf16_f32 v134, v136, v137
	v_cvt_pk_bf16_f32 v135, v139, v141
	v_cvt_pk_bf16_f32 v136, v138, v140
	v_cvt_pk_bf16_f32 v137, v142, v143
	v_cvt_pk_bf16_f32 v138, v144, v145
	v_cvt_pk_bf16_f32 v139, v147, v149
	s_waitcnt lgkmcnt(8)
	v_mfma_f32_32x32x16_bf16 v[16:31], v[110:113], v[182:185], v[16:31]
	ds_read_b64_tr_b16 v[110:111], v96 offset:32832
	ds_read_b64_tr_b16 v[112:113], v96 offset:34368
	ds_read_b64_tr_b16 v[140:141], v96 offset:35904
	ds_read_b64_tr_b16 v[142:143], v96 offset:37440
	v_exp_f32_e32 v162, v51
	v_exp_f32_e32 v163, v36
	v_exp_f32_e32 v164, v52
	s_waitcnt lgkmcnt(10)
	v_mfma_f32_32x32x16_bf16 v[0:15], v[106:109], v[182:185], v[0:15]
	ds_read_b64_tr_b16 v[106:107], v96 offset:32768
	ds_read_b64_tr_b16 v[108:109], v96 offset:34304
	v_exp_f32_e32 v165, v37
	v_exp_f32_e32 v166, v53
	v_exp_f32_e32 v167, v38
	v_exp_f32_e32 v168, v54
	v_exp_f32_e32 v169, v39
	s_waitcnt lgkmcnt(8)
	v_mfma_f32_32x32x16_bf16 v[16:31], v[102:105], v[158:161], v[16:31]
	ds_read_b64_tr_b16 v[102:103], v96 offset:35840
	ds_read_b64_tr_b16 v[104:105], v96 offset:37376
	v_exp_f32_e32 v170, v55
	v_exp_f32_e32 v171, v40
	v_exp_f32_e32 v153, v32
	v_exp_f32_e32 v154, v48
	s_waitcnt lgkmcnt(8)
	v_mfma_f32_32x32x16_bf16 v[0:15], v[98:101], v[158:161], v[0:15]
	ds_read_b128 v[216:219], v131 offset:4608
	ds_read_b128 v[220:223], v131
	v_exp_f32_e32 v155, v33
	v_exp_f32_e32 v158, v49
	v_exp_f32_e32 v159, v34
	v_exp_f32_e32 v160, v50
	s_waitcnt lgkmcnt(4)
	v_mfma_f32_32x32x16_bf16 v[16:31], v[106:109], v[132:135], v[16:31]
	ds_read_b128 v[224:227], v131 offset:32
	ds_read_b128 v[228:231], v131 offset:64
	v_exp_f32_e32 v161, v35
	v_exp_f32_e32 v173, v56
	v_exp_f32_e32 v180, v41
	v_exp_f32_e32 v181, v57
	v_mfma_f32_32x32x16_bf16 v[0:15], v[110:113], v[132:135], v[0:15]
	ds_read_b128 v[236:239], v131 offset:96
	ds_read_b128 v[240:243], v131 offset:4640
	v_exp_f32_e32 v182, v42
	v_exp_f32_e32 v183, v58
	v_exp_f32_e32 v184, v43
	v_exp_f32_e32 v185, v59
	s_waitcnt lgkmcnt(6)
	v_mfma_f32_32x32x16_bf16 v[16:31], v[102:105], v[136:139], v[16:31]
	ds_read_b128 v[244:247], v131 offset:4672
	ds_read_b128 v[248:251], v131 offset:4704
	v_exp_f32_e32 v186, v44
	v_exp_f32_e32 v187, v60
	v_exp_f32_e32 v188, v45
	v_exp_f32_e32 v189, v61
	v_mfma_f32_32x32x16_bf16 v[0:15], v[140:143], v[136:139], v[0:15]
	v_exp_f32_e32 v190, v46
	v_exp_f32_e32 v191, v62
	v_exp_f32_e32 v192, v47
	v_exp_f32_e32 v193, v63
	s_setprio 0
	s_waitcnt lgkmcnt(0)
	s_barrier
; template <int DK, int PAR, bool HASNEXT, bool LDK, bool LDV, bool STK> ...
;     ...
; #pragma unroll
;         for (int ds = 0; ds < A::NDS; ++ds) {
;             kf[ds][0] = *(const LAS bf16x8*)(Kb + aoffk + ds * 32);
;             kf[ds][1] = *(const LAS bf16x8*)(Kb + aoffk + 32 * A::KSTR + ds * 32);
;         }
;     }
;     s16x4 vlo[4][2], vhi[4][2];
; #pragma unroll
;     for (int j = 0; j < 2; ++j) {
;         vlo[j][0] = vtr(Vb + aoffv + j * 16 * A::VSTR); vhi[j][0] = vtr(Vb + aoffv + (j * 16 + 8) * A::VSTR);
;         vlo[j][1] = vtr(Vb + aoffv + j * 16 * A::VSTR + 64); vhi[j][1] = vtr(Vb + aoffv + (j * 16 + 8) * A::VSTR + 64);
;     }
;     if (HASNEXT) {
;         f32x16 z;
; #pragma unroll
;         for (int i = 0; i < 16; ++i) z[i] = 0.f;
; #pragma unroll
;         for (int ds = 0; ds < A::NDS; ++ds) {
;             N0 = __builtin_amdgcn_mfma_f32_32x32x16_bf16(kf[ds][0], qf[ds], ds == 0 ? z : N0, 0, 0, 0);
;             N1 = __builtin_amdgcn_mfma_f32_32x32x16_bf16(kf[ds][1], qf[ds], ds == 0 ? z : N1, 0, 0, 0);
;         }
;     }
; #pragma unroll
;     for (int i = 0; i < 16; ++i) { l += C0[i]; l += C1[i]; }
;     bf16x8 pb[4];
;     { u32x4 w;
;       w.x = pk2(C0[0], C0[1]); w.y = pk2(C0[2], C0[3]); w.z = pk2(C0[4], C0[5]); w.w = pk2(C0[6], C0[7]); pb[0] = __builtin_bit_cast(bf16x8, w);
;       w.x = pk2(C0[8], C0[9]); w.y = pk2(C0[10], C0[11]); w.z = pk2(C0[12], C0[13]); w.w = pk2(C0[14], C0[15]); pb[1] = __builtin_bit_cast(bf16x8, w);
;       w.x = pk2(C1[0], C1[1]); w.y = pk2(C1[2], C1[3]); w.z = pk2(C1[4], C1[5]); w.w = pk2(C1[6], C1[7]); pb[2] = __builtin_bit_cast(bf16x8, w);
;       w.x = pk2(C1[8], C1[9]); w.y = pk2(C1[10], C1[11]); w.z = pk2(C1[12], C1[13]); w.w = pk2(C1[14], C1[15]); pb[3] = __builtin_bit_cast(bf16x8, w); }
;     if (HASNEXT) {
;         constexpr int VPER = (DK == 64) ? 6 : 4;
; #pragma unroll
;         for (int g = 0; g < 2 * A::NDS; ++g) { __builtin_amdgcn_sched_group_barrier(0x008, 1, 0); __builtin_amdgcn_sched_group_barrier(0x002, VPER, 0); }
;     }
;     asm volatile("" : "+v"(l));
;     __builtin_amdgcn_sched_barrier(0);
; #pragma unroll
;     for (int j = 2; j < 4; ++j) {
;         vlo[j][0] = vtr(Vb + aoffv + j * 16 * A::VSTR); vhi[j][0] = vtr(Vb + aoffv + (j * 16 + 8) * A::VSTR);
;         vlo[j][1] = vtr(Vb + aoffv + j * 16 * A::VSTR + 64); vhi[j][1] = vtr(Vb + aoffv + (j * 16 + 8) * A::VSTR + 64);
;     }
	s_setprio 1
	s_mov_b32 s11, 0x23a34000
	ds_read_b64_tr_b16 v[110:111], v96 offset:38912
	ds_read_b64_tr_b16 v[112:113], v96 offset:40448
	v_mfma_f32_32x32x16_bf16 v[48:63], v[216:219], v[76:79], 0
	v_add_co_u32_e32 v32, vcc, s11, v126
	s_mov_b32 s11, 0x24aac000
	s_nop 0
	v_addc_co_u32_e32 v33, vcc, 0, v127, vcc
	global_load_dwordx4 v[80:83], v[32:33], off
	v_add_co_u32_e32 v32, vcc, s11, v128
	ds_read_b64_tr_b16 v[106:107], v96 offset:38976
	s_nop 0
	v_addc_co_u32_e32 v33, vcc, 0, v129, vcc
	global_load_dwordx4 v[84:87], v[32:33], off
	v_mfma_f32_32x32x16_bf16 v[32:47], v[220:223], v[76:79], 0
	ds_read_b64_tr_b16 v[108:109], v96 offset:40512
	ds_read_b64_tr_b16 v[102:103], v96 offset:41984
	ds_read_b64_tr_b16 v[104:105], v96 offset:43520
	ds_read_b64_tr_b16 v[98:99], v96 offset:42048
	ds_read_b64_tr_b16 v[100:101], v96 offset:43584
	v_add_f32_e32 v126, v153, v152
	v_add_f32_e32 v126, v154, v126
	v_add_f32_e32 v126, v155, v126
	v_add_f32_e32 v126, v158, v126
	v_add_f32_e32 v126, v159, v126
	v_mfma_f32_32x32x16_bf16 v[32:47], v[224:227], v[72:75], v[32:47]
	v_add_f32_e32 v126, v160, v126
	v_add_f32_e32 v126, v161, v126
	v_add_f32_e32 v126, v162, v126
	v_add_f32_e32 v126, v163, v126
	v_add_f32_e32 v126, v164, v126
	v_mfma_f32_32x32x16_bf16 v[32:47], v[228:231], v[68:71], v[32:47]
	s_waitcnt vmcnt(3)
	ds_write_b128 v130, v[88:91]
	s_waitcnt vmcnt(2)
	ds_write_b128 v117, v[92:95] offset:26624
	v_add_f32_e32 v126, v165, v126
	v_add_f32_e32 v126, v166, v126
	v_add_f32_e32 v126, v167, v126
	v_add_f32_e32 v126, v168, v126
	v_add_f32_e32 v126, v169, v126
	v_mfma_f32_32x32x16_bf16 v[32:47], v[236:239], v[64:67], v[32:47]
	v_add_f32_e32 v126, v170, v126
	v_add_f32_e32 v126, v171, v126
	v_add_f32_e32 v126, v173, v126
	v_add_f32_e32 v126, v180, v126
	v_cvt_pk_bf16_f32 v144, v164, v166
	v_cvt_pk_bf16_f32 v145, v168, v170
	v_cvt_pk_bf16_f32 v136, v186, v188
	v_cvt_pk_bf16_f32 v137, v190, v192
	v_mfma_f32_32x32x16_bf16 v[48:63], v[240:243], v[72:75], v[48:63]
	v_add_f32_e32 v126, v181, v126
	v_add_f32_e32 v126, v182, v126
	v_add_f32_e32 v126, v183, v126
	v_add_f32_e32 v126, v184, v126
	v_cvt_pk_bf16_f32 v134, v171, v180
	v_cvt_pk_bf16_f32 v135, v182, v184
	v_mfma_f32_32x32x16_bf16 v[48:63], v[244:247], v[68:71], v[48:63]
	v_add_f32_e32 v126, v185, v126
	v_add_f32_e32 v126, v186, v126
	v_add_f32_e32 v126, v187, v126
	v_add_f32_e32 v126, v188, v126
	v_cvt_pk_bf16_f32 v142, v154, v158
	v_cvt_pk_bf16_f32 v143, v160, v162
	v_mfma_f32_32x32x16_bf16 v[48:63], v[248:251], v[64:67], v[48:63]
	v_add_f32_e32 v126, v189, v126
	v_add_f32_e32 v126, v190, v126
	v_add_f32_e32 v126, v191, v126
	v_add_f32_e32 v126, v192, v126
	v_add_f32_e32 v172, v193, v126
	v_cvt_pk_bf16_f32 v126, v153, v155
	v_cvt_pk_bf16_f32 v127, v159, v161
	v_cvt_pk_bf16_f32 v128, v163, v165
	v_cvt_pk_bf16_f32 v129, v167, v169
	v_cvt_pk_bf16_f32 v182, v173, v181
	v_cvt_pk_bf16_f32 v183, v183, v185
	v_cvt_pk_bf16_f32 v184, v187, v189
	v_cvt_pk_bf16_f32 v185, v191, v193
	s_waitcnt lgkmcnt(8)
	v_mfma_f32_32x32x16_bf16 v[16:31], v[110:113], v[126:129], v[16:31]
	ds_read_b64_tr_b16 v[110:111], v96 offset:45120
	ds_read_b64_tr_b16 v[112:113], v96 offset:46656
	v_exp_f32_e32 v146, v32
	v_exp_f32_e32 v132, v48
	v_exp_f32_e32 v148, v33
	v_exp_f32_e32 v133, v49
	v_exp_f32_e32 v158, v34
	s_waitcnt lgkmcnt(8)
	v_mfma_f32_32x32x16_bf16 v[0:15], v[106:109], v[126:129], v[0:15]
	ds_read_b64_tr_b16 v[106:107], v96 offset:45056
	ds_read_b64_tr_b16 v[108:109], v96 offset:46592
	ds_read_b64_tr_b16 v[126:127], v96 offset:48192
	ds_read_b64_tr_b16 v[128:129], v96 offset:49728
	v_exp_f32_e32 v159, v35
	v_exp_f32_e32 v160, v36
	v_exp_f32_e32 v162, v37
	s_waitcnt lgkmcnt(10)
	v_mfma_f32_32x32x16_bf16 v[16:31], v[102:105], v[134:137], v[16:31]
	ds_read_b64_tr_b16 v[102:103], v96 offset:48128
	ds_read_b64_tr_b16 v[104:105], v96 offset:49664
	v_exp_f32_e32 v164, v38
	v_exp_f32_e32 v139, v54
	v_exp_f32_e32 v166, v39
	v_exp_f32_e32 v141, v55
	s_waitcnt lgkmcnt(10)
	v_mfma_f32_32x32x16_bf16 v[0:15], v[98:101], v[134:137], v[0:15]
	ds_read_b128 v[216:219], v131 offset:17920
	ds_read_b128 v[220:223], v131 offset:13312
	v_exp_f32_e32 v161, v40
	v_exp_f32_e32 v134, v50
	v_exp_f32_e32 v135, v51
	v_exp_f32_e32 v136, v52
	s_waitcnt lgkmcnt(6)
	v_mfma_f32_32x32x16_bf16 v[16:31], v[106:109], v[142:145], v[16:31]
	ds_read_b128 v[224:227], v131 offset:13344
	ds_read_b128 v[228:231], v131 offset:17952
	v_exp_f32_e32 v137, v53
	v_exp_f32_e32 v138, v56
	v_exp_f32_e32 v163, v41
	v_exp_f32_e32 v140, v57
	v_mfma_f32_32x32x16_bf16 v[0:15], v[110:113], v[142:145], v[0:15]
	ds_read_b128 v[236:239], v131 offset:13376
	ds_read_b128 v[240:243], v131 offset:17984
	v_exp_f32_e32 v165, v42
	v_exp_f32_e32 v168, v43
	v_exp_f32_e32 v167, v44
	v_exp_f32_e32 v169, v45
	s_waitcnt lgkmcnt(6)
	v_mfma_f32_32x32x16_bf16 v[16:31], v[102:105], v[182:185], v[16:31]
	ds_read_b128 v[244:247], v131 offset:13408
	ds_read_b128 v[248:251], v131 offset:18016
	v_exp_f32_e32 v170, v46
	v_exp_f32_e32 v147, v62
	v_exp_f32_e32 v171, v47
	v_exp_f32_e32 v142, v58
	v_mfma_f32_32x32x16_bf16 v[0:15], v[126:129], v[182:185], v[0:15]
	v_exp_f32_e32 v143, v59
	v_exp_f32_e32 v144, v60
	v_exp_f32_e32 v145, v61
	v_exp_f32_e32 v149, v63
	s_setprio 0
	s_waitcnt lgkmcnt(0)
	s_barrier
	s_add_i32 s10, s10, 2
	v_lshl_add_u64 v[122:123], v[122:123], 0, s[34:35]
	s_cmpk_lt_u32 s10, 0x7e
	v_lshl_add_u64 v[124:125], v[124:125], 0, s[34:35]
	s_cbranch_scc1 .LBB0_779
; template <int DK, int PAR, bool HASNEXT, bool LDK, bool LDV, bool STK> ...
;     ...
;     if (LDK) { ldk0 = *(const u32x4*)(kg0 + (size_t)(t + 3) * kstep); if (has1) ldk1 = *(const u32x4*)(kg1 + (size_t)(t + 3) * kstep); }
;     if (LDV) ldv = *(const u32x4*)(vg + (size_t)(t + 2) * vstep);
;     bf16x8 kf[A::NDS][2];
;     if (HASNEXT) {
; #pragma unroll
;         for (int ds = 0; ds < A::NDS; ++ds) {
;             kf[ds][0] = *(const LAS bf16x8*)(Kb + aoffk + ds * 32);
;             kf[ds][1] = *(const LAS bf16x8*)(Kb + aoffk + 32 * A::KSTR + ds * 32);
;         }
;     }
;     s16x4 vlo[4][2], vhi[4][2];
; #pragma unroll
;     for (int j = 0; j < 2; ++j) {
;         vlo[j][0] = vtr(Vb + aoffv + j * 16 * A::VSTR); vhi[j][0] = vtr(Vb + aoffv + (j * 16 + 8) * A::VSTR);
;         vlo[j][1] = vtr(Vb + aoffv + j * 16 * A::VSTR + 64); vhi[j][1] = vtr(Vb + aoffv + (j * 16 + 8) * A::VSTR + 64);
;     }
;     if (HASNEXT) {
;         f32x16 z;
; #pragma unroll
;         for (int i = 0; i < 16; ++i) z[i] = 0.f;
; #pragma unroll
;         for (int ds = 0; ds < A::NDS; ++ds) {
;             N0 = __builtin_amdgcn_mfma_f32_32x32x16_bf16(kf[ds][0], qf[ds], ds == 0 ? z : N0, 0, 0, 0);
;             N1 = __builtin_amdgcn_mfma_f32_32x32x16_bf16(kf[ds][1], qf[ds], ds == 0 ? z : N1, 0, 0, 0);
;         }
;     }
; #pragma unroll
;     for (int i = 0; i < 16; ++i) { l += C0[i]; l += C1[i]; }
;     bf16x8 pb[4];
;     { u32x4 w;
;       w.x = pk2(C0[0], C0[1]); w.y = pk2(C0[2], C0[3]); w.z = pk2(C0[4], C0[5]); w.w = pk2(C0[6], C0[7]); pb[0] = __builtin_bit_cast(bf16x8, w);
;       w.x = pk2(C0[8], C0[9]); w.y = pk2(C0[10], C0[11]); w.z = pk2(C0[12], C0[13]); w.w = pk2(C0[14], C0[15]); pb[1] = __builtin_bit_cast(bf16x8, w);
;       w.x = pk2(C1[0], C1[1]); w.y = pk2(C1[2], C1[3]); w.z = pk2(C1[4], C1[5]); w.w = pk2(C1[6], C1[7]); pb[2] = __builtin_bit_cast(bf16x8, w);
;       w.x = pk2(C1[8], C1[9]); w.y = pk2(C1[10], C1[11]); w.z = pk2(C1[12], C1[13]); w.w = pk2(C1[14], C1[15]); pb[3] = __builtin_bit_cast(bf16x8, w); }
;     if (HASNEXT) {
;         constexpr int VPER = (DK == 64) ? 6 : 4;
; #pragma unroll
;         for (int g = 0; g < 2 * A::NDS; ++g) { __builtin_amdgcn_sched_group_barrier(0x008, 1, 0); __builtin_amdgcn_sched_group_barrier(0x002, VPER, 0); }
;     }
;     asm volatile("" : "+v"(l));
;     __builtin_amdgcn_sched_barrier(0);
; #pragma unroll
	s_waitcnt vmcnt(0)
	ds_read_b128 v[80:83], v130
	s_waitcnt lgkmcnt(0)
	s_setprio 1
	ds_read_b128 v[48:51], v131 offset:17920
	ds_read_b128 v[124:127], v131 offset:17952
	ds_read_b128 v[182:185], v131 offset:13376
	ds_read_b128 v[186:189], v131 offset:17984
	ds_read_b128 v[190:193], v131 offset:13408
	ds_read_b128 v[194:197], v131 offset:18016
	ds_read_b64_tr_b16 v[110:111], v96 offset:26624
	ds_read_b64_tr_b16 v[112:113], v96 offset:28160
	ds_read_b64_tr_b16 v[106:107], v96 offset:26688
	s_waitcnt lgkmcnt(8)
	v_mfma_f32_32x32x16_bf16 v[48:63], v[48:51], v[76:79], 0
	v_add_co_u32_e32 v32, vcc, 0x20c000, v120
	ds_read_b64_tr_b16 v[108:109], v96 offset:28224
	s_nop 0
	v_addc_co_u32_e32 v33, vcc, 0, v121, vcc
	global_load_dwordx4 v[88:91], v[32:33], off
	v_add_co_u32_e32 v32, vcc, 0x208000, v118
	ds_read_b128 v[120:123], v131 offset:13344
	s_nop 0
	v_addc_co_u32_e32 v33, vcc, 0, v119, vcc
	global_load_dwordx4 v[92:95], v[32:33], off
	ds_read_b128 v[32:35], v131 offset:13312
	s_waitcnt lgkmcnt(0)
	v_mfma_f32_32x32x16_bf16 v[32:47], v[32:35], v[76:79], 0
	ds_read_b64_tr_b16 v[102:103], v96 offset:29696
	ds_read_b64_tr_b16 v[104:105], v96 offset:31232
	ds_read_b64_tr_b16 v[98:99], v96 offset:29760
	ds_read_b64_tr_b16 v[100:101], v96 offset:31296
	v_mfma_f32_32x32x16_bf16 v[32:47], v[120:123], v[72:75], v[32:47]
	v_add_f32_e32 v120, v146, v172
	v_add_f32_e32 v120, v132, v120
	v_cvt_pk_bf16_f32 v132, v132, v133
	v_add_f32_e32 v120, v148, v120
	v_add_f32_e32 v120, v133, v120
	v_cvt_pk_bf16_f32 v133, v134, v135
	v_add_f32_e32 v120, v158, v120
	v_add_f32_e32 v120, v134, v120
	v_cvt_pk_bf16_f32 v134, v136, v137
	v_add_f32_e32 v120, v159, v120
	v_add_f32_e32 v120, v135, v120
	v_cvt_pk_bf16_f32 v135, v139, v141
	v_mfma_f32_32x32x16_bf16 v[48:63], v[124:127], v[72:75], v[48:63]
	v_cvt_pk_bf16_f32 v124, v161, v163
	v_cvt_pk_bf16_f32 v125, v165, v168
	v_cvt_pk_bf16_f32 v126, v167, v169
	v_cvt_pk_bf16_f32 v127, v170, v171
	v_add_f32_e32 v120, v160, v120
	v_add_f32_e32 v120, v136, v120
	v_add_f32_e32 v120, v162, v120
	v_add_f32_e32 v120, v137, v120
	v_mfma_f32_32x32x16_bf16 v[32:47], v[182:185], v[68:71], v[32:47]
	v_add_f32_e32 v120, v164, v120
	v_add_f32_e32 v120, v139, v120
	v_add_f32_e32 v120, v166, v120
	v_add_f32_e32 v120, v141, v120
	v_add_f32_e32 v120, v161, v120
	v_add_f32_e32 v120, v138, v120
	v_cvt_pk_bf16_f32 v136, v138, v140
	v_mfma_f32_32x32x16_bf16 v[48:63], v[186:189], v[68:71], v[48:63]
	v_add_f32_e32 v120, v163, v120
	v_add_f32_e32 v120, v140, v120
	v_add_f32_e32 v120, v165, v120
	v_add_f32_e32 v120, v142, v120
	v_add_f32_e32 v120, v168, v120
	v_add_f32_e32 v120, v143, v120
	v_cvt_pk_bf16_f32 v137, v142, v143
	v_mfma_f32_32x32x16_bf16 v[32:47], v[190:193], v[64:67], v[32:47]
	v_add_f32_e32 v120, v167, v120
	v_add_f32_e32 v120, v144, v120
	v_add_f32_e32 v120, v169, v120
	v_add_f32_e32 v120, v145, v120
	v_add_f32_e32 v120, v170, v120
	v_add_f32_e32 v120, v147, v120
	v_cvt_pk_bf16_f32 v138, v144, v145
	v_mfma_f32_32x32x16_bf16 v[48:63], v[194:197], v[64:67], v[48:63]
	v_add_f32_e32 v120, v171, v120
	v_add_f32_e32 v128, v149, v120
	v_cvt_pk_bf16_f32 v120, v146, v148
	v_cvt_pk_bf16_f32 v121, v158, v159
	v_cvt_pk_bf16_f32 v122, v160, v162
	v_cvt_pk_bf16_f32 v123, v164, v166
	v_cvt_pk_bf16_f32 v139, v147, v149
	s_nop 0
	v_mfma_f32_32x32x16_bf16 v[16:31], v[110:113], v[120:123], v[16:31]
	ds_read_b64_tr_b16 v[110:111], v96 offset:32832
	ds_read_b64_tr_b16 v[112:113], v96 offset:34368
	v_exp_f32_e32 v140, v32
	v_exp_f32_e32 v141, v48
	v_exp_f32_e32 v142, v33
	v_exp_f32_e32 v143, v49
	v_exp_f32_e32 v144, v34
	v_mfma_f32_32x32x16_bf16 v[0:15], v[106:109], v[120:123], v[0:15]
	ds_read_b64_tr_b16 v[106:107], v96 offset:32768
	ds_read_b64_tr_b16 v[108:109], v96 offset:34304
	ds_read_b64_tr_b16 v[120:121], v96 offset:35904
	ds_read_b64_tr_b16 v[122:123], v96 offset:37440
	v_exp_f32_e32 v145, v50
	v_exp_f32_e32 v146, v35
	v_exp_f32_e32 v147, v51
	s_waitcnt lgkmcnt(8)
	v_mfma_f32_32x32x16_bf16 v[16:31], v[102:105], v[124:127], v[16:31]
	ds_read_b64_tr_b16 v[102:103], v96 offset:35840
	ds_read_b64_tr_b16 v[104:105], v96 offset:37376
	v_exp_f32_e32 v148, v36
	v_exp_f32_e32 v149, v52
	v_exp_f32_e32 v150, v37
	v_exp_f32_e32 v151, v53
	v_exp_f32_e32 v152, v38
	s_waitcnt lgkmcnt(8)
	v_mfma_f32_32x32x16_bf16 v[0:15], v[98:101], v[124:127], v[0:15]
	v_exp_f32_e32 v153, v54
	v_exp_f32_e32 v154, v39
	v_exp_f32_e32 v155, v55
	v_exp_f32_e32 v158, v40
	v_exp_f32_e32 v159, v58
	v_exp_f32_e32 v160, v43
	v_exp_f32_e32 v161, v59
	s_waitcnt lgkmcnt(4)
	v_mfma_f32_32x32x16_bf16 v[16:31], v[106:109], v[132:135], v[16:31]
	v_exp_f32_e32 v162, v44
	v_exp_f32_e32 v163, v60
	v_exp_f32_e32 v164, v45
	v_exp_f32_e32 v165, v61
	v_exp_f32_e32 v166, v46
	v_exp_f32_e32 v167, v62
	v_exp_f32_e32 v168, v47
	v_mfma_f32_32x32x16_bf16 v[0:15], v[110:113], v[132:135], v[0:15]
	v_exp_f32_e32 v132, v56
	v_exp_f32_e32 v133, v41
	v_exp_f32_e32 v134, v57
	v_exp_f32_e32 v135, v42
	v_exp_f32_e32 v169, v63
	s_waitcnt lgkmcnt(0)
	v_mfma_f32_32x32x16_bf16 v[16:31], v[102:105], v[136:139], v[16:31]
	v_mfma_f32_32x32x16_bf16 v[0:15], v[120:123], v[136:139], v[0:15]
	s_setprio 0
	s_waitcnt vmcnt(3)
	ds_write_b128 v130, v[80:83]
	s_waitcnt vmcnt(2)
	ds_write_b128 v117, v[84:87] offset:38912
	s_waitcnt lgkmcnt(0)
	s_barrier
; template <int DK, int PAR, bool HASNEXT, bool LDK, bool LDV, bool STK> ...
;     ...
;     if (LDK) { ldk0 = *(const u32x4*)(kg0 + (size_t)(t + 3) * kstep); if (has1) ldk1 = *(const u32x4*)(kg1 + (size_t)(t + 3) * kstep); }
;     if (LDV) ldv = *(const u32x4*)(vg + (size_t)(t + 2) * vstep);
;     bf16x8 kf[A::NDS][2];
;     if (HASNEXT) {
; #pragma unroll
;         for (int ds = 0; ds < A::NDS; ++ds) {
;             kf[ds][0] = *(const LAS bf16x8*)(Kb + aoffk + ds * 32);
;             kf[ds][1] = *(const LAS bf16x8*)(Kb + aoffk + 32 * A::KSTR + ds * 32);
;         }
;     }
;     s16x4 vlo[4][2], vhi[4][2];
; #pragma unroll
;     for (int j = 0; j < 2; ++j) {
;         vlo[j][0] = vtr(Vb + aoffv + j * 16 * A::VSTR); vhi[j][0] = vtr(Vb + aoffv + (j * 16 + 8) * A::VSTR);
;         vlo[j][1] = vtr(Vb + aoffv + j * 16 * A::VSTR + 64); vhi[j][1] = vtr(Vb + aoffv + (j * 16 + 8) * A::VSTR + 64);
;     }
;     if (HASNEXT) {
;         f32x16 z;
; #pragma unroll
;         for (int i = 0; i < 16; ++i) z[i] = 0.f;
; #pragma unroll
;         for (int ds = 0; ds < A::NDS; ++ds) {
;             N0 = __builtin_amdgcn_mfma_f32_32x32x16_bf16(kf[ds][0], qf[ds], ds == 0 ? z : N0, 0, 0, 0);
;             N1 = __builtin_amdgcn_mfma_f32_32x32x16_bf16(kf[ds][1], qf[ds], ds == 0 ? z : N1, 0, 0, 0);
;         }
;     }
; #pragma unroll
;     for (int i = 0; i < 16; ++i) { l += C0[i]; l += C1[i]; }
;     bf16x8 pb[4];
;     { u32x4 w;
;       w.x = pk2(C0[0], C0[1]); w.y = pk2(C0[2], C0[3]); w.z = pk2(C0[4], C0[5]); w.w = pk2(C0[6], C0[7]); pb[0] = __builtin_bit_cast(bf16x8, w);
;       w.x = pk2(C0[8], C0[9]); w.y = pk2(C0[10], C0[11]); w.z = pk2(C0[12], C0[13]); w.w = pk2(C0[14], C0[15]); pb[1] = __builtin_bit_cast(bf16x8, w);
;       w.x = pk2(C1[0], C1[1]); w.y = pk2(C1[2], C1[3]); w.z = pk2(C1[4], C1[5]); w.w = pk2(C1[6], C1[7]); pb[2] = __builtin_bit_cast(bf16x8, w);
;       w.x = pk2(C1[8], C1[9]); w.y = pk2(C1[10], C1[11]); w.z = pk2(C1[12], C1[13]); w.w = pk2(C1[14], C1[15]); pb[3] = __builtin_bit_cast(bf16x8, w); }
;     if (HASNEXT) {
;         constexpr int VPER = (DK == 64) ? 6 : 4;
; #pragma unroll
;         for (int g = 0; g < 2 * A::NDS; ++g) { __builtin_amdgcn_sched_group_barrier(0x008, 1, 0); __builtin_amdgcn_sched_group_barrier(0x002, VPER, 0); }
;     }
;     asm volatile("" : "+v"(l));
;     __builtin_amdgcn_sched_barrier(0);
; #pragma unroll
	s_setprio 1
	ds_read_b128 v[32:35], v131
	s_mov_b32 s8, 0x20c000
	ds_read_b128 v[84:87], v131 offset:32
	ds_read_b128 v[98:101], v131 offset:4640
	ds_read_b128 v[102:105], v131 offset:64
	ds_read_b128 v[106:109], v131 offset:4672
	ds_read_b128 v[110:113], v131 offset:96
	ds_read_b64_tr_b16 v[122:123], v96 offset:38912
	ds_read_b64_tr_b16 v[124:125], v96 offset:40448
	s_waitcnt lgkmcnt(7)
	v_mfma_f32_32x32x16_bf16 v[32:47], v[32:35], v[76:79], 0
	v_add_co_u32_e32 v48, vcc, s8, v118
	v_add_f32_e32 v52, v140, v128
	s_nop 0
	v_addc_co_u32_e32 v49, vcc, 0, v119, vcc
	global_load_dwordx4 v[80:83], v[48:49], off
	ds_read_b128 v[48:51], v131 offset:4608
	v_add_f32_e32 v52, v141, v52
	v_add_f32_e32 v52, v142, v52
	v_add_f32_e32 v128, v143, v52
	s_waitcnt lgkmcnt(0)
	v_mfma_f32_32x32x16_bf16 v[48:63], v[48:51], v[76:79], 0
	v_add_f32_e32 v128, v144, v128
	v_add_f32_e32 v128, v145, v128
	v_add_f32_e32 v128, v146, v128
	v_add_f32_e32 v128, v147, v128
	v_add_f32_e32 v128, v148, v128
	v_add_f32_e32 v136, v149, v128
	ds_read_b128 v[118:121], v131 offset:4704
	v_mfma_f32_32x32x16_bf16 v[32:47], v[84:87], v[72:75], v[32:47]
	v_add_f32_e32 v84, v150, v136
	v_add_f32_e32 v84, v151, v84
	v_add_f32_e32 v84, v152, v84
	v_add_f32_e32 v84, v153, v84
	v_add_f32_e32 v84, v154, v84
	v_add_f32_e32 v86, v155, v84
	ds_read_b64_tr_b16 v[126:127], v96 offset:38976
	v_mfma_f32_32x32x16_bf16 v[48:63], v[98:101], v[72:75], v[48:63]
	v_add_f32_e32 v86, v158, v86
	v_add_f32_e32 v86, v132, v86
	v_add_f32_e32 v86, v133, v86
	v_add_f32_e32 v86, v134, v86
	v_add_f32_e32 v86, v135, v86
	v_add_f32_e32 v98, v159, v86
	ds_read_b64_tr_b16 v[128:129], v96 offset:40512
	v_mfma_f32_32x32x16_bf16 v[32:47], v[102:105], v[68:71], v[32:47]
	v_add_f32_e32 v98, v160, v98
	v_add_f32_e32 v98, v161, v98
	v_add_f32_e32 v98, v162, v98
	v_add_f32_e32 v98, v163, v98
	v_add_f32_e32 v98, v164, v98
	v_add_f32_e32 v100, v165, v98
	ds_read_b64_tr_b16 v[84:85], v96 offset:41984
	v_mfma_f32_32x32x16_bf16 v[48:63], v[106:109], v[68:71], v[48:63]
	v_add_f32_e32 v100, v166, v100
	v_add_f32_e32 v100, v167, v100
	v_add_f32_e32 v100, v168, v100
	ds_read_b64_tr_b16 v[86:87], v96 offset:43520
	ds_read_b64_tr_b16 v[98:99], v96 offset:42048
	v_add_f32_e32 v136, v169, v100
	ds_read_b64_tr_b16 v[100:101], v96 offset:43584
	v_cvt_pk_bf16_f32 v102, v140, v142
	v_cvt_pk_bf16_f32 v103, v144, v146
	v_mfma_f32_32x32x16_bf16 v[32:47], v[110:113], v[64:67], v[32:47]
	v_cvt_pk_bf16_f32 v104, v148, v150
	v_cvt_pk_bf16_f32 v105, v152, v154
	v_cvt_pk_bf16_f32 v106, v158, v133
	v_cvt_pk_bf16_f32 v107, v135, v160
	v_cvt_pk_bf16_f32 v108, v162, v164
	v_cvt_pk_bf16_f32 v109, v166, v168
	s_waitcnt lgkmcnt(6)
	v_mfma_f32_32x32x16_bf16 v[48:63], v[118:121], v[64:67], v[48:63]
	v_cvt_pk_bf16_f32 v110, v141, v143
	v_cvt_pk_bf16_f32 v111, v145, v147
	v_cvt_pk_bf16_f32 v112, v149, v151
	v_cvt_pk_bf16_f32 v113, v153, v155
	v_cvt_pk_bf16_f32 v118, v132, v134
	v_cvt_pk_bf16_f32 v119, v159, v161
	v_cvt_pk_bf16_f32 v120, v163, v165
	v_cvt_pk_bf16_f32 v121, v167, v169
	v_mfma_f32_32x32x16_bf16 v[16:31], v[122:125], v[102:105], v[16:31]
	ds_read_b64_tr_b16 v[122:123], v96 offset:45120
	ds_read_b64_tr_b16 v[124:125], v96 offset:46656
	v_exp_f32_e32 v132, v32
	v_exp_f32_e32 v133, v48
	v_exp_f32_e32 v134, v33
	v_exp_f32_e32 v135, v49
	v_exp_f32_e32 v137, v34
	s_waitcnt lgkmcnt(6)
	v_mfma_f32_32x32x16_bf16 v[0:15], v[126:129], v[102:105], v[0:15]
	ds_read_b64_tr_b16 v[102:103], v96 offset:45056
	ds_read_b64_tr_b16 v[104:105], v96 offset:46592
	ds_read_b64_tr_b16 v[126:127], v96 offset:48192
	ds_read_b64_tr_b16 v[128:129], v96 offset:49728
	v_exp_f32_e32 v138, v50
	v_exp_f32_e32 v139, v35
	v_exp_f32_e32 v140, v51
	s_waitcnt lgkmcnt(8)
	v_mfma_f32_32x32x16_bf16 v[16:31], v[84:87], v[106:109], v[16:31]
	ds_read_b64_tr_b16 v[84:85], v96 offset:48128
	ds_read_b64_tr_b16 v[86:87], v96 offset:49664
	v_exp_f32_e32 v141, v36
	v_exp_f32_e32 v142, v52
	v_exp_f32_e32 v143, v37
	v_exp_f32_e32 v144, v53
	v_exp_f32_e32 v145, v38
	s_waitcnt lgkmcnt(8)
	v_mfma_f32_32x32x16_bf16 v[0:15], v[98:101], v[106:109], v[0:15]
	v_exp_f32_e32 v146, v54
	v_exp_f32_e32 v147, v39
	v_exp_f32_e32 v148, v55
	v_exp_f32_e32 v149, v40
	v_exp_f32_e32 v150, v58
	v_exp_f32_e32 v151, v43
	v_exp_f32_e32 v152, v59
	s_waitcnt lgkmcnt(4)
	v_mfma_f32_32x32x16_bf16 v[16:31], v[102:105], v[110:113], v[16:31]
	v_exp_f32_e32 v153, v44
	v_exp_f32_e32 v154, v60
	v_exp_f32_e32 v155, v45
	v_exp_f32_e32 v158, v61
	v_exp_f32_e32 v159, v46
	v_exp_f32_e32 v160, v62
	v_exp_f32_e32 v161, v47
	v_mfma_f32_32x32x16_bf16 v[0:15], v[122:125], v[110:113], v[0:15]
	v_exp_f32_e32 v122, v56
	v_exp_f32_e32 v123, v41
	v_exp_f32_e32 v124, v57
	v_exp_f32_e32 v125, v42
	v_exp_f32_e32 v162, v63
	s_waitcnt lgkmcnt(0)
	v_mfma_f32_32x32x16_bf16 v[16:31], v[84:87], v[118:121], v[16:31]
	v_mfma_f32_32x32x16_bf16 v[0:15], v[126:129], v[118:121], v[0:15]
	s_setprio 0
	s_waitcnt vmcnt(2)
	ds_write_b128 v130, v[88:91] offset:13312
	s_waitcnt vmcnt(1)
	ds_write_b128 v117, v[92:95] offset:26624
	s_waitcnt lgkmcnt(0)
	s_barrier
; template <int DK, int PAR, bool HASNEXT, bool LDK, bool LDV, bool STK> ...
;     ...
;             kf[ds][0] = *(const LAS bf16x8*)(Kb + aoffk + ds * 32);
;             kf[ds][1] = *(const LAS bf16x8*)(Kb + aoffk + 32 * A::KSTR + ds * 32);
;         }
;     }
;     s16x4 vlo[4][2], vhi[4][2];
; #pragma unroll
;     for (int j = 0; j < 2; ++j) {
;         vlo[j][0] = vtr(Vb + aoffv + j * 16 * A::VSTR); vhi[j][0] = vtr(Vb + aoffv + (j * 16 + 8) * A::VSTR);
;         vlo[j][1] = vtr(Vb + aoffv + j * 16 * A::VSTR + 64); vhi[j][1] = vtr(Vb + aoffv + (j * 16 + 8) * A::VSTR + 64);
;     }
;     if (HASNEXT) {
;         f32x16 z;
; #pragma unroll
;         for (int i = 0; i < 16; ++i) z[i] = 0.f;
; #pragma unroll
;         for (int ds = 0; ds < A::NDS; ++ds) {
;             N0 = __builtin_amdgcn_mfma_f32_32x32x16_bf16(kf[ds][0], qf[ds], ds == 0 ? z : N0, 0, 0, 0);
;             N1 = __builtin_amdgcn_mfma_f32_32x32x16_bf16(kf[ds][1], qf[ds], ds == 0 ? z : N1, 0, 0, 0);
;         }
;     }
; #pragma unroll
;     for (int i = 0; i < 16; ++i) { l += C0[i]; l += C1[i]; }
;     bf16x8 pb[4];
;     { u32x4 w;
;       w.x = pk2(C0[0], C0[1]); w.y = pk2(C0[2], C0[3]); w.z = pk2(C0[4], C0[5]); w.w = pk2(C0[6], C0[7]); pb[0] = __builtin_bit_cast(bf16x8, w);
;       w.x = pk2(C0[8], C0[9]); w.y = pk2(C0[10], C0[11]); w.z = pk2(C0[12], C0[13]); w.w = pk2(C0[14], C0[15]); pb[1] = __builtin_bit_cast(bf16x8, w);
;       w.x = pk2(C1[0], C1[1]); w.y = pk2(C1[2], C1[3]); w.z = pk2(C1[4], C1[5]); w.w = pk2(C1[6], C1[7]); pb[2] = __builtin_bit_cast(bf16x8, w);
;       w.x = pk2(C1[8], C1[9]); w.y = pk2(C1[10], C1[11]); w.z = pk2(C1[12], C1[13]); w.w = pk2(C1[14], C1[15]); pb[3] = __builtin_bit_cast(bf16x8, w); }
;     if (HASNEXT) {
;         constexpr int VPER = (DK == 64) ? 6 : 4;
; #pragma unroll
;         for (int g = 0; g < 2 * A::NDS; ++g) { __builtin_amdgcn_sched_group_barrier(0x008, 1, 0); __builtin_amdgcn_sched_group_barrier(0x002, VPER, 0); }
;     }
;     asm volatile("" : "+v"(l));
;     __builtin_amdgcn_sched_barrier(0);
; #pragma unroll
;     for (int j = 2; j < 4; ++j) {
;         vlo[j][0] = vtr(Vb + aoffv + j * 16 * A::VSTR); vhi[j][0] = vtr(Vb + aoffv + (j * 16 + 8) * A::VSTR);
;         vlo[j][1] = vtr(Vb + aoffv + j * 16 * A::VSTR + 64); vhi[j][1] = vtr(Vb + aoffv + (j * 16 + 8) * A::VSTR + 64);
;     }
; #pragma unroll
;     for (int j = 0; j < 4; ++j) {
	s_setprio 1
	ds_read_b128 v[32:35], v131 offset:13312
	ds_read_b128 v[48:51], v131 offset:17920
	ds_read_b128 v[84:87], v131 offset:13344
	ds_read_b128 v[88:91], v131 offset:17952
	ds_read_b128 v[92:95], v131 offset:13376
	ds_read_b128 v[98:101], v131 offset:17984
	ds_read_b128 v[102:105], v131 offset:13408
	ds_read_b128 v[106:109], v131 offset:18016
	ds_read_b64_tr_b16 v[110:111], v96 offset:26624
	s_waitcnt lgkmcnt(8)
	v_mfma_f32_32x32x16_bf16 v[32:47], v[32:35], v[76:79], 0
	v_add_f32_e32 v52, v132, v136
	v_add_f32_e32 v52, v133, v52
	v_add_f32_e32 v52, v134, v52
	v_add_f32_e32 v52, v135, v52
	v_add_f32_e32 v52, v137, v52
	v_add_f32_e32 v118, v138, v52
	ds_read_b64_tr_b16 v[112:113], v96 offset:28160
	s_waitcnt lgkmcnt(8)
	v_mfma_f32_32x32x16_bf16 v[48:63], v[48:51], v[76:79], 0
	v_add_f32_e32 v78, v139, v118
	v_add_f32_e32 v78, v140, v78
	v_add_f32_e32 v78, v141, v78
	v_add_f32_e32 v78, v142, v78
	v_add_f32_e32 v78, v143, v78
	v_add_f32_e32 v118, v144, v78
	ds_read_b64_tr_b16 v[76:77], v96 offset:26688
	s_waitcnt lgkmcnt(8)
	v_mfma_f32_32x32x16_bf16 v[32:47], v[84:87], v[72:75], v[32:47]
	v_add_f32_e32 v84, v145, v118
	v_add_f32_e32 v84, v146, v84
	v_add_f32_e32 v84, v147, v84
	v_add_f32_e32 v84, v148, v84
	v_add_f32_e32 v84, v149, v84
	v_add_f32_e32 v84, v122, v84
	ds_read_b64_tr_b16 v[78:79], v96 offset:28224
	s_waitcnt lgkmcnt(8)
	v_mfma_f32_32x32x16_bf16 v[48:63], v[88:91], v[72:75], v[48:63]
	v_add_f32_e32 v74, v123, v84
	v_add_f32_e32 v74, v124, v74
	v_add_f32_e32 v74, v125, v74
	v_add_f32_e32 v74, v150, v74
	v_add_f32_e32 v74, v151, v74
	v_add_f32_e32 v84, v152, v74
	ds_read_b64_tr_b16 v[72:73], v96 offset:29696
	s_waitcnt lgkmcnt(8)
	v_mfma_f32_32x32x16_bf16 v[32:47], v[92:95], v[68:71], v[32:47]
	v_add_f32_e32 v84, v153, v84
	v_add_f32_e32 v84, v154, v84
	v_add_f32_e32 v84, v155, v84
	v_add_f32_e32 v84, v158, v84
	v_add_f32_e32 v84, v159, v84
	v_add_f32_e32 v84, v160, v84
	ds_read_b64_tr_b16 v[74:75], v96 offset:31232
	s_waitcnt lgkmcnt(8)
	v_mfma_f32_32x32x16_bf16 v[48:63], v[98:101], v[68:71], v[48:63]
	v_add_f32_e32 v70, v161, v84
	ds_read_b64_tr_b16 v[68:69], v96 offset:29760
	v_add_f32_e32 v118, v162, v70
	ds_read_b64_tr_b16 v[70:71], v96 offset:31296
	v_cvt_pk_bf16_f32 v84, v132, v134
	v_cvt_pk_bf16_f32 v85, v137, v139
	v_cvt_pk_bf16_f32 v86, v141, v143
	v_cvt_pk_bf16_f32 v87, v145, v147
	s_waitcnt lgkmcnt(9)
	v_mfma_f32_32x32x16_bf16 v[32:47], v[102:105], v[64:67], v[32:47]
	v_cvt_pk_bf16_f32 v88, v149, v123
	v_cvt_pk_bf16_f32 v89, v125, v151
	v_cvt_pk_bf16_f32 v90, v153, v155
	v_cvt_pk_bf16_f32 v91, v159, v161
	v_cvt_pk_bf16_f32 v92, v133, v135
	v_cvt_pk_bf16_f32 v93, v138, v140
	s_waitcnt lgkmcnt(8)
	v_mfma_f32_32x32x16_bf16 v[48:63], v[106:109], v[64:67], v[48:63]
	v_cvt_pk_bf16_f32 v94, v142, v144
	v_cvt_pk_bf16_f32 v95, v146, v148
	v_cvt_pk_bf16_f32 v64, v122, v124
	v_cvt_pk_bf16_f32 v65, v150, v152
	v_cvt_pk_bf16_f32 v66, v154, v158
	v_cvt_pk_bf16_f32 v67, v160, v162
	s_waitcnt lgkmcnt(6)
	v_mfma_f32_32x32x16_bf16 v[16:31], v[110:113], v[84:87], v[16:31]
	ds_read_b64_tr_b16 v[98:99], v96 offset:35904
	ds_read_b64_tr_b16 v[100:101], v96 offset:37440
	v_exp_f32_e32 v102, v32
	s_nop 0
	v_exp_f32_e32 v103, v48
	v_exp_f32_e32 v48, v33
	v_exp_f32_e32 v63, v63
	s_waitcnt lgkmcnt(6)
	v_mfma_f32_32x32x16_bf16 v[0:15], v[76:79], v[84:87], v[0:15]
	ds_read_b64_tr_b16 v[76:77], v96 offset:32768
	ds_read_b64_tr_b16 v[78:79], v96 offset:34304
	ds_read_b64_tr_b16 v[84:85], v96 offset:32832
	ds_read_b64_tr_b16 v[86:87], v96 offset:34368
	s_waitcnt lgkmcnt(8)
	v_mfma_f32_32x32x16_bf16 v[16:31], v[72:75], v[88:91], v[16:31]
	ds_read_b64_tr_b16 v[72:73], v96 offset:35840
	ds_read_b64_tr_b16 v[74:75], v96 offset:37376
	s_waitcnt lgkmcnt(8)
	v_mfma_f32_32x32x16_bf16 v[0:15], v[68:71], v[88:91], v[0:15]
	v_exp_f32_e32 v68, v49
	v_exp_f32_e32 v49, v34
	v_exp_f32_e32 v69, v50
	v_exp_f32_e32 v50, v35
	v_exp_f32_e32 v70, v51
	v_exp_f32_e32 v51, v36
	v_exp_f32_e32 v71, v52
	s_waitcnt lgkmcnt(4)
	v_mfma_f32_32x32x16_bf16 v[16:31], v[76:79], v[92:95], v[16:31]
	v_exp_f32_e32 v52, v37
	v_exp_f32_e32 v76, v53
	v_exp_f32_e32 v53, v38
	v_exp_f32_e32 v77, v54
	v_exp_f32_e32 v54, v39
	v_exp_f32_e32 v78, v55
	v_exp_f32_e32 v55, v40
	s_waitcnt lgkmcnt(2)
	v_mfma_f32_32x32x16_bf16 v[0:15], v[84:87], v[92:95], v[0:15]
	v_exp_f32_e32 v79, v56
	v_exp_f32_e32 v56, v41
	v_exp_f32_e32 v84, v57
	v_exp_f32_e32 v57, v42
	v_exp_f32_e32 v85, v58
	v_exp_f32_e32 v58, v43
	v_exp_f32_e32 v86, v59
	s_waitcnt lgkmcnt(0)
	v_mfma_f32_32x32x16_bf16 v[16:31], v[72:75], v[64:67], v[16:31]
	v_exp_f32_e32 v59, v44
	v_exp_f32_e32 v72, v60
	v_exp_f32_e32 v60, v45
	v_exp_f32_e32 v73, v61
	v_exp_f32_e32 v61, v46
	v_exp_f32_e32 v74, v62
	v_exp_f32_e32 v62, v47
	v_mfma_f32_32x32x16_bf16 v[0:15], v[98:101], v[64:67], v[0:15]
	s_setprio 0
	s_waitcnt vmcnt(0)
	ds_write_b128 v117, v[80:83] offset:38912
	s_waitcnt lgkmcnt(0)
	s_barrier
; template <int DK, int PAR, bool HASNEXT, bool LDK, bool LDV, bool STK> ...
;     ...
; #pragma unroll
;     for (int i = 0; i < 16; ++i) { l += C0[i]; l += C1[i]; }
;     bf16x8 pb[4];
;     { u32x4 w;
;       w.x = pk2(C0[0], C0[1]); w.y = pk2(C0[2], C0[3]); w.z = pk2(C0[4], C0[5]); w.w = pk2(C0[6], C0[7]); pb[0] = __builtin_bit_cast(bf16x8, w);
;       w.x = pk2(C0[8], C0[9]); w.y = pk2(C0[10], C0[11]); w.z = pk2(C0[12], C0[13]); w.w = pk2(C0[14], C0[15]); pb[1] = __builtin_bit_cast(bf16x8, w);
;       w.x = pk2(C1[0], C1[1]); w.y = pk2(C1[2], C1[3]); w.z = pk2(C1[4], C1[5]); w.w = pk2(C1[6], C1[7]); pb[2] = __builtin_bit_cast(bf16x8, w);
;       w.x = pk2(C1[8], C1[9]); w.y = pk2(C1[10], C1[11]); w.z = pk2(C1[12], C1[13]); w.w = pk2(C1[14], C1[15]); pb[3] = __builtin_bit_cast(bf16x8, w); }
;     if (HASNEXT) {
;         constexpr int VPER = (DK == 64) ? 6 : 4;
; #pragma unroll
;         for (int g = 0; g < 2 * A::NDS; ++g) { __builtin_amdgcn_sched_group_barrier(0x008, 1, 0); __builtin_amdgcn_sched_group_barrier(0x002, VPER, 0); }
;     }
;     asm volatile("" : "+v"(l));
;     __builtin_amdgcn_sched_barrier(0);
; #pragma unroll
;     for (int j = 2; j < 4; ++j) {
;         vlo[j][0] = vtr(Vb + aoffv + j * 16 * A::VSTR); vhi[j][0] = vtr(Vb + aoffv + (j * 16 + 8) * A::VSTR);
;         vlo[j][1] = vtr(Vb + aoffv + j * 16 * A::VSTR + 64); vhi[j][1] = vtr(Vb + aoffv + (j * 16 + 8) * A::VSTR + 64);
;     }
; #pragma unroll
;     for (int j = 0; j < 4; ++j) {
;         const bf16x8 a0 = __builtin_shufflevector(vlo[j][0], vhi[j][0], 0, 1, 2, 3, 4, 5, 6, 7);
;         const bf16x8 a1 = __builtin_shufflevector(vlo[j][1], vhi[j][1], 0, 1, 2, 3, 4, 5, 6, 7);
;         o0 = __builtin_amdgcn_mfma_f32_32x32x16_bf16(a0, pb[j], o0, 0, 0, 0);
;         o1 = __builtin_amdgcn_mfma_f32_32x32x16_bf16(a1, pb[j], o1, 0, 0, 0);
;     }
;     if (HASNEXT) {
; #pragma unroll
;         for (int i = 0; i < 16; ++i) { N0[i] = __builtin_amdgcn_exp2f(N0[i]); N1[i] = __builtin_amdgcn_exp2f(N1[i]); }
; #pragma unroll
;         for (int g = 0; g < 8; ++g) { __builtin_amdgcn_sched_group_barrier(0x008, 1, 0); __builtin_amdgcn_sched_group_barrier(0x002, 4, 0); }
;     }
;     __builtin_amdgcn_sched_barrier(0);
;     __builtin_amdgcn_s_setprio(0);
;     if (STK) { LAS unsigned char* Kn = lds + PAR * A::KBUF; *(LAS u32x4*)(Kn + kl0) = stk0; if (has1) *(LAS u32x4*)(Kn + kl1) = stk1; }
	s_setprio 1
	v_add_f32_e32 v64, v102, v118
	v_add_f32_e32 v64, v103, v64
	v_add_f32_e32 v64, v48, v64
	v_add_f32_e32 v64, v68, v64
	v_add_f32_e32 v64, v49, v64
	v_add_f32_e32 v64, v69, v64
	v_add_f32_e32 v64, v50, v64
	v_add_f32_e32 v64, v70, v64
	v_add_f32_e32 v64, v51, v64
	v_add_f32_e32 v64, v71, v64
	v_add_f32_e32 v64, v52, v64
	v_add_f32_e32 v64, v76, v64
	v_add_f32_e32 v64, v53, v64
	v_add_f32_e32 v64, v77, v64
	v_add_f32_e32 v64, v54, v64
	v_add_f32_e32 v64, v78, v64
	v_add_f32_e32 v64, v55, v64
	v_add_f32_e32 v64, v79, v64
	v_add_f32_e32 v64, v56, v64
	v_add_f32_e32 v64, v84, v64
	v_add_f32_e32 v64, v57, v64
	v_add_f32_e32 v64, v85, v64
	v_add_f32_e32 v64, v58, v64
	v_add_f32_e32 v64, v86, v64
	v_add_f32_e32 v64, v59, v64
	v_add_f32_e32 v64, v72, v64
	v_add_f32_e32 v64, v60, v64
	v_add_f32_e32 v64, v73, v64
	ds_read_b64_tr_b16 v[32:33], v96 offset:38912
	ds_read_b64_tr_b16 v[34:35], v96 offset:40448
	ds_read_b64_tr_b16 v[38:39], v96 offset:40512
	ds_read_b64_tr_b16 v[36:37], v96 offset:38976
	ds_read_b64_tr_b16 v[40:41], v96 offset:41984
	ds_read_b64_tr_b16 v[42:43], v96 offset:43520
	ds_read_b64_tr_b16 v[46:47], v96 offset:43584
	ds_read_b64_tr_b16 v[44:45], v96 offset:42048
	v_add_f32_e32 v64, v61, v64
	v_add_f32_e32 v64, v74, v64
	v_add_f32_e32 v64, v62, v64
	v_add_f32_e32 v64, v63, v64
	v_cvt_pk_bf16_f32 v48, v102, v48
	v_cvt_pk_bf16_f32 v49, v49, v50
	v_cvt_pk_bf16_f32 v50, v51, v52
	v_cvt_pk_bf16_f32 v51, v53, v54
	v_cvt_pk_bf16_f32 v52, v55, v56
	v_cvt_pk_bf16_f32 v53, v57, v58
	v_cvt_pk_bf16_f32 v54, v59, v60
	v_cvt_pk_bf16_f32 v55, v61, v62
	v_cvt_pk_bf16_f32 v56, v103, v68
	v_cvt_pk_bf16_f32 v57, v69, v70
	v_cvt_pk_bf16_f32 v58, v71, v76
	v_cvt_pk_bf16_f32 v59, v77, v78
	v_cvt_pk_bf16_f32 v60, v79, v84
	v_cvt_pk_bf16_f32 v61, v85, v86
	v_cvt_pk_bf16_f32 v62, v72, v73
	v_cvt_pk_bf16_f32 v63, v74, v63
	s_waitcnt lgkmcnt(6)
	v_mfma_f32_32x32x16_bf16 v[16:31], v[32:35], v[48:51], v[16:31]
	ds_read_b64_tr_b16 v[32:33], v96 offset:45056
	ds_read_b64_tr_b16 v[34:35], v96 offset:46592
	s_waitcnt lgkmcnt(6)
	v_mfma_f32_32x32x16_bf16 v[0:15], v[36:39], v[48:51], v[0:15]
	ds_read_b64_tr_b16 v[38:39], v96 offset:46656
	ds_read_b64_tr_b16 v[36:37], v96 offset:45120
	s_waitcnt lgkmcnt(6)
	v_mfma_f32_32x32x16_bf16 v[16:31], v[40:43], v[52:55], v[16:31]
	s_waitcnt lgkmcnt(4)
	v_mfma_f32_32x32x16_bf16 v[0:15], v[44:47], v[52:55], v[0:15]
	s_waitcnt lgkmcnt(2)
	v_mfma_f32_32x32x16_bf16 v[16:31], v[32:35], v[56:59], v[16:31]
	ds_read_b64_tr_b16 v[32:33], v96 offset:48128
	ds_read_b64_tr_b16 v[34:35], v96 offset:49664
	s_waitcnt lgkmcnt(2)
	v_mfma_f32_32x32x16_bf16 v[0:15], v[36:39], v[56:59], v[0:15]
	ds_read_b64_tr_b16 v[38:39], v96 offset:49728
	ds_read_b64_tr_b16 v[36:37], v96 offset:48192
	s_waitcnt lgkmcnt(2)
	v_mfma_f32_32x32x16_bf16 v[16:31], v[32:35], v[60:63], v[16:31]
	s_waitcnt lgkmcnt(0)
	v_mfma_f32_32x32x16_bf16 v[0:15], v[36:39], v[60:63], v[0:15]
	s_setprio 0
	v_mov_b32_e32 v32, v64
	s_nop 1
	v_permlane32_swap_b32_e32 v64, v32
	v_add_f32_e32 v32, v64, v32
	v_div_scale_f32 v33, s[8:9], v32, v32, 1.0
	v_rcp_f32_e32 v34, v33
	v_lshlrev_b32_e32 v96, 1, v116
	s_waitcnt lgkmcnt(0)
	s_barrier
	v_fma_f32 v35, -v33, v34, 1.0
	v_fmac_f32_e32 v34, v35, v34
	v_div_scale_f32 v35, vcc, 1.0, v32, 1.0
	v_mul_f32_e32 v36, v35, v34
	v_fma_f32 v37, -v33, v36, v35
	v_fmac_f32_e32 v36, v37, v34
	v_fma_f32 v33, -v33, v36, v35
	v_div_fmas_f32 v33, v33, v34, v36
	v_div_fixup_f32 v32, v33, v32, 1.0
	v_pk_mul_f32 v[16:17], v[16:17], v[32:33] op_sel_hi:[1,0]
	v_pk_mul_f32 v[18:19], v[18:19], v[32:33] op_sel_hi:[1,0]
	v_pk_mul_f32 v[0:1], v[0:1], v[32:33] op_sel_hi:[1,0]
	v_pk_mul_f32 v[2:3], v[2:3], v[32:33] op_sel_hi:[1,0]
	v_lshlrev_b64 v[34:35], 11, v[114:115]
	v_cvt_pk_bf16_f32 v16, v16, v17
	v_cvt_pk_bf16_f32 v17, v18, v19
	v_pk_mul_f32 v[18:19], v[20:21], v[32:33] op_sel_hi:[1,0]
	v_pk_mul_f32 v[20:21], v[22:23], v[32:33] op_sel_hi:[1,0]
	v_cvt_pk_bf16_f32 v0, v0, v1
	v_cvt_pk_bf16_f32 v1, v2, v3
	v_pk_mul_f32 v[2:3], v[4:5], v[32:33] op_sel_hi:[1,0]
	v_pk_mul_f32 v[4:5], v[6:7], v[32:33] op_sel_hi:[1,0]
	v_lshl_add_u64 v[34:35], s[6:7], 0, v[34:35]
	v_cvt_pk_bf16_f32 v18, v18, v19
	v_cvt_pk_bf16_f32 v19, v20, v21
	v_cvt_pk_bf16_f32 v2, v2, v3
	v_cvt_pk_bf16_f32 v3, v4, v5
	v_lshl_add_u64 v[34:35], v[34:35], 0, v[96:97]
	v_permlane32_swap_b32_e32 v16, v18
	v_permlane32_swap_b32_e32 v17, v19
	v_permlane32_swap_b32_e32 v0, v2
	v_permlane32_swap_b32_e32 v1, v3
	global_store_dwordx4 v[34:35], v[16:19], off
	global_store_dwordx4 v[34:35], v[0:3], off offset:64
	v_pk_mul_f32 v[20:21], v[30:31], v[32:33] op_sel_hi:[1,0]
	v_pk_mul_f32 v[16:17], v[24:25], v[32:33] op_sel_hi:[1,0]
	v_pk_mul_f32 v[18:19], v[26:27], v[32:33] op_sel_hi:[1,0]
	v_pk_mul_f32 v[0:1], v[8:9], v[32:33] op_sel_hi:[1,0]
	v_pk_mul_f32 v[2:3], v[10:11], v[32:33] op_sel_hi:[1,0]
	v_cvt_pk_bf16_f32 v16, v16, v17
	v_cvt_pk_bf16_f32 v17, v18, v19
	v_pk_mul_f32 v[18:19], v[28:29], v[32:33] op_sel_hi:[1,0]
	v_cvt_pk_bf16_f32 v0, v0, v1
	v_cvt_pk_bf16_f32 v1, v2, v3
	v_pk_mul_f32 v[2:3], v[12:13], v[32:33] op_sel_hi:[1,0]
	v_pk_mul_f32 v[4:5], v[14:15], v[32:33] op_sel_hi:[1,0]
	v_cvt_pk_bf16_f32 v18, v18, v19
	v_cvt_pk_bf16_f32 v19, v20, v21
	v_cvt_pk_bf16_f32 v2, v2, v3
	v_cvt_pk_bf16_f32 v3, v4, v5
	v_permlane32_swap_b32_e32 v16, v18
	v_permlane32_swap_b32_e32 v17, v19
	v_permlane32_swap_b32_e32 v0, v2
	v_permlane32_swap_b32_e32 v1, v3
	global_store_dwordx4 v[34:35], v[16:19], off offset:32
	global_store_dwordx4 v[34:35], v[0:3], off offset:96
	s_branch .LBB0_740
